# combination + counted wait at the S5 prompt sub-chunk loop latch (output stores stay in flight)
# speedup vs baseline: 1.0062x; 1.0034x over previous
; DEVINL float bf2f(u16 h) { return __uint_as_float(((unsigned)h) << 16); }
; DEVINL f32x4 mfma16(bf16x8 a, bf16x8 b, f32x4 c) { return __builtin_amdgcn_mfma_f32_16x16x32_bf16(a, b, c, 0, 0, 0); }
; DEVINL void s5_seg(const Params& p, char* wsm, int rb, int ntok, int g, float& hr, float& hi, bool outp) {
;     ...
;   const int tk0 = (lane >> 4) * 4, ucol = g * 16 + (lane & 15);
;   bf16x8 a_nxt = zero8;
;   u16 u_nxt[4] = {0, 0, 0, 0};
;   {
;     const int nt0 = min(16, ntok);
;     if ((lane >> 4) < 2 && (lane & 15) < nt0)
;       a_nxt = *(const bf16x8*)(ub + (size_t)(rb + (lane & 15)) * 512 + g * 16 + 8 * (lane >> 4));
;     if (outp && tk0 < nt0) {
; #pragma unroll
;       for (int j = 0; j < 4; ++j) u_nxt[j] = ub[(size_t)(rb + tk0 + j) * 512 + ucol];
;     }
;   }
;   for (int t0 = 0; t0 < ntok; t0 += 16) {
;     const int nt = min(16, ntok - t0);
;     const bf16x8 a = a_nxt;
;     u16 u_cur[4];
; #pragma unroll
;     for (int j = 0; j < 4; ++j) u_cur[j] = u_nxt[j];
;     if (t0 + 16 < ntok) {
;       const int ntn = min(16, ntok - t0 - 16);
;       a_nxt = zero8;
;       if ((lane >> 4) < 2 && (lane & 15) < ntn)
;         a_nxt = *(const bf16x8*)(ub + (size_t)(rb + t0 + 16 + (lane & 15)) * 512 + g * 16 + 8 * (lane >> 4));
;       if (outp && tk0 < ntn) {
; #pragma unroll
;         for (int j = 0; j < 4; ++j) u_nxt[j] = ub[(size_t)(rb + t0 + 16 + tk0 + j) * 512 + ucol];
;       }
;     }
;     ...
;     if (outp) {
;       f32x4 y = f32x4{0, 0, 0, 0};
; #pragma unroll
;       for (int ks = 0; ks < 4; ++ks) {
;         bf16x8 ha = *(const bf16x8*)(Hs + (lane & 15) * 136 + ks * 32 + 8 * (lane >> 4));
;         y = mfma16(ha, cm[ks], y);
;       }
;       if (tk0 < nt) {
;         float yv[4];
; #pragma unroll
;         for (int j = 0; j < 4; ++j) yv[j] = geluf_(y[j] + dsk * bf2f(u_cur[j]));
;         store_pairs(yg, 512, rb + t0 + tk0, ucol, yv[0], yv[1], yv[2], yv[3]);
;       }
;       __builtin_amdgcn_wave_barrier();
;       asm volatile("s_waitcnt lgkmcnt(0)" ::: "memory");
;     }
.LBB0_519:
	s_or_b64 exec, exec, s[0:1]
	v_lshlrev_b32_e32 v83, 2, v74
	v_or_b32_e32 v4, v83, v91
	s_movk_i32 s0, 0x3200
	v_ashrrev_i32_e32 v5, 31, v4
	v_mul_lo_u32 v3, v68, s0
	v_lshl_add_u64 v[68:69], v[54:55], 1, s[96:97]
	v_lshlrev_b64 v[76:77], 10, v[4:5]
	v_lshl_add_u64 v[76:77], v[68:69], 0, v[76:77]
	global_load_ushort v108, v[76:77], off
	v_or_b32_e32 v76, 1, v4
	v_ashrrev_i32_e32 v77, 31, v76
	v_lshlrev_b64 v[76:77], 10, v[76:77]
	v_lshl_add_u64 v[76:77], v[68:69], 0, v[76:77]
	global_load_ushort v105, v[76:77], off
	v_or_b32_e32 v76, 2, v4
	v_or_b32_e32 v4, 3, v4
	v_ashrrev_i32_e32 v77, 31, v76
	v_ashrrev_i32_e32 v5, 31, v4
	v_lshlrev_b64 v[76:77], 10, v[76:77]
	v_lshlrev_b64 v[4:5], 10, v[4:5]
	v_lshl_add_u64 v[76:77], v[68:69], 0, v[76:77]
	v_lshl_add_u64 v[4:5], v[68:69], 0, v[4:5]
	global_load_ushort v90, v[76:77], off
	global_load_ushort v88, v[4:5], off
	v_lshl_add_u64 v[4:5], v[70:71], 1, s[96:97]
	v_lshl_add_u64 v[70:71], v[56:57], 1, v[4:5]
	v_lshlrev_b32_e32 v4, 2, v73
	v_sub_u32_e32 v55, 0, v4
	v_mul_u32_u24_e32 v4, 0x110, v81
	v_lshlrev_b32_e32 v5, 1, v56
	v_add3_u32 v86, v3, v4, v5
	v_and_b32_e32 v4, -2, v54
	v_readlane_b32 s0, v194, 29
	v_ashrrev_i32_e32 v5, 31, v4
	v_readlane_b32 s1, v194, 30
	v_lshl_or_b32 v85, v73, 3, v3
	v_and_b32_e32 v56, 1, v72
	v_lshl_add_u64 v[72:73], v[4:5], 1, s[0:1]
	s_movk_i32 s0, 0x840
	v_add3_u32 v89, v91, v81, 16
	v_add_u32_e32 v91, v91, v83
	v_cndmask_b32_e64 v84, v124, v125, s[34:35]
	v_cmp_eq_u32_e64 s[34:35], 0, v56
	v_mad_u32_u24 v3, v74, s0, v3
	v_lshl_add_u32 v102, v56, 1, v91
	v_add_u32_e32 v106, v85, v55
	s_waitcnt vmcnt(4)
	v_mov_b64_e32 v[54:55], v[58:59]
	s_mov_b32 s66, 0
	v_lshl_or_b32 v87, v81, 2, v3
	v_mov_b32_e32 v74, v65
	v_pk_mov_b32 v[76:77], v[64:65], v[64:65] op_sel:[1,0]
	s_mov_b64 s[44:45], 0
	v_mov_b32_e32 v107, v84
	v_mov_b64_e32 v[56:57], v[60:61]
	s_waitcnt vmcnt(3)
	v_mov_b32_e32 v3, v108
	s_waitcnt vmcnt(2)
	v_mov_b32_e32 v4, v105
	s_waitcnt vmcnt(1)
	v_mov_b32_e32 v5, v90
	s_waitcnt vmcnt(0)
	v_mov_b32_e32 v109, v88
	s_branch .LBB0_521
.LS5C_nostore:
	s_waitcnt vmcnt(0)
.LBB0_520:
	s_or_b64 exec, exec, s[38:39]
	s_waitcnt lgkmcnt(0)
	s_waitcnt vmcnt(2)
	s_nop 3
	v_mov_b64_e32 v[60:61], v[56:57]
	v_add_u32_e32 v107, -16, v107
	v_mov_b32_e32 v108, v3
	v_mov_b32_e32 v105, v4
	v_mov_b32_e32 v90, v5
	v_mov_b32_e32 v88, v109
	v_mov_b64_e32 v[58:59], v[54:55]
	s_mov_b32 s66, s67
	s_andn2_b64 exec, exec, s[44:45]
	s_cbranch_execz .LBB0_529
